# P4 v-expansion epilogue: transposed V image staged through LDS for coalesced stores
# baseline (speedup 1.0000x reference)
; __device__ __forceinline__ unsigned pk2(float lo, float hi) { f32v2_t v = {lo, hi}; bf16v2_t r = __builtin_convertvector(v, bf16v2_t); return __builtin_bit_cast(unsigned, r); }
; __device__ __forceinline__ void vt_store(bf16_t* vt_row, int key32, const f32x16& a, int hh) {
; #pragma unroll
;   for (int g = 0; g < 4; ++g) {
;     const int pos = key32 + (g >> 1) * 16 + hh * 8 + (g & 1) * 4;
;     u32x2 w; w.x = pk2(a[4 * g], a[4 * g + 1]); w.y = pk2(a[4 * g + 2], a[4 * g + 3]);
;     *(u32x2*)(vt_row + pos) = w;
;   }
; }
; __device__ void phase_mla_expand(const Params& p, char* lds) {
;     ...
;       for (int i = 0; i < 2; ++i)
; #pragma unroll
;         for (int j = 0; j < 2; ++j) {
;           const int mb = m0 + wr * 64 + i * 32; const int nn = n0 - 1024 + wc * 64 + j * 32 + l31;
;           bf16_t* vt; int key32;
;           if (mb < TP) { const int b = mb >> 12; vt = (bf16_t*)(ws + W_D2) + ((size_t)(b * 1024 + nn)) * SEQP; key32 = mb & 4095; }
;           else { const int x = mb - TP; const int b = x / LKS; vt = (bf16_t*)(ws + W_D2 + SZ_VTP) + ((size_t)(b * 1024 + nn)) * LKS; key32 = x - b * LKS; }
;           vt_store(vt, key32, acc[i][j], hh);
.LBB0_548:
	v_and_b32_e32 v151, 63, v181
	v_lshrrev_b32_e32 v150, 6, v181
	v_and_b32_e32 v152, 31, v151
	v_lshrrev_b32_e32 v153, 5, v151
	v_mul_u32_u24_e32 v153, 0x440, v153
	v_mul_u32_u24_e32 v143, 0x2200, v150
	v_lshl_add_u32 v142, v152, 2, v153
	v_add_u32_e32 v142, v142, v143
	v_add_u32_e32 v142, 0x8000, v142
	v_add_u32_e32 v143, 0x8000, v143
	v_and_b32_e32 v144, 3, v151
	v_lshrrev_b32_e32 v145, 2, v151
	v_and_b32_e32 v152, 1, v144
	v_lshrrev_b32_e32 v153, 1, v144
	v_mul_u32_u24_e32 v152, 0x440, v152
	v_mul_u32_u24_e32 v153, 0x1100, v153
	v_add3_u32 v148, v143, v152, v153
	v_lshl_add_u32 v148, v145, 2, v148
	s_sub_i32 s0, s39, 0x400
	v_and_b32_e32 v152, 1, v150
	v_lshl_add_u32 v152, v152, 6, v145
	v_add_u32_e32 v152, s0, v152
	v_lshrrev_b32_e32 v153, 1, v150
	s_cmp_lt_i32 s38, 0x8000
	s_cbranch_scc0 .Lp4v_samp
	s_lshr_b32 s0, s38, 12
	s_lshl_b32 s0, s0, 10
	v_add_u32_e32 v152, s0, v152
	s_and_b32 s0, s38, 0xfff
	v_lshl_add_u32 v155, v153, 6, s0
	s_movk_i32 s1, 0x2080
	s_mov_b32 vcc_lo, 0x1079e000
	s_branch .Lp4v_go
.Lp4v_samp:
	s_sub_i32 s0, s38, 0x8000
	v_lshl_add_u32 v155, v153, 6, s0
	v_mul_hi_u32 v154, v155, s83
	v_lshrrev_b32_e32 v154, 9, v154
	v_mul_u32_u24_e32 v153, 0x840, v154
	v_sub_u32_e32 v155, v155, v153
	v_lshl_add_u32 v152, v154, 10, v152
	s_movk_i32 s1, 0x1080
	s_mov_b32 vcc_lo, 0x1489e000
; __device__ __forceinline__ unsigned pk2(float lo, float hi) { f32v2_t v = {lo, hi}; bf16v2_t r = __builtin_convertvector(v, bf16v2_t); return __builtin_bit_cast(unsigned, r); }
; __device__ __forceinline__ void vt_store(bf16_t* vt_row, int key32, const f32x16& a, int hh) {
; #pragma unroll
;   for (int g = 0; g < 4; ++g) {
;     const int pos = key32 + (g >> 1) * 16 + hh * 8 + (g & 1) * 4;
;     u32x2 w; w.x = pk2(a[4 * g], a[4 * g + 1]); w.y = pk2(a[4 * g + 2], a[4 * g + 3]);
;     *(u32x2*)(vt_row + pos) = w;
;   }
; }
; __device__ void phase_mla_expand(const Params& p, char* lds) {
;     ...
;       for (int i = 0; i < 2; ++i)
; #pragma unroll
;         for (int j = 0; j < 2; ++j) {
;           const int mb = m0 + wr * 64 + i * 32; const int nn = n0 - 1024 + wc * 64 + j * 32 + l31;
;           bf16_t* vt; int key32;
;           if (mb < TP) { const int b = mb >> 12; vt = (bf16_t*)(ws + W_D2) + ((size_t)(b * 1024 + nn)) * SEQP; key32 = mb & 4095; }
;           else { const int x = mb - TP; const int b = x / LKS; vt = (bf16_t*)(ws + W_D2 + SZ_VTP) + ((size_t)(b * 1024 + nn)) * LKS; key32 = x - b * LKS; }
;           vt_store(vt, key32, acc[i][j], hh);
;         }
.Lp4v_go:
	v_mul_lo_u32 v149, v152, s1
	v_lshl_add_u32 v155, v144, 3, v155
	v_lshl_add_u32 v149, v155, 1, v149
	v_add_u32_e32 v149, vcc_lo, v149
	s_lshl_b32 s0, s1, 4
	ds_write_b32 v142, v48 offset:0
	ds_write_b32 v142, v49 offset:272
	ds_write_b32 v142, v50 offset:544
	ds_write_b32 v142, v51 offset:816
	ds_write_b32 v142, v52 offset:2176
	ds_write_b32 v142, v53 offset:2448
	ds_write_b32 v142, v54 offset:2720
	ds_write_b32 v142, v55 offset:2992
	ds_write_b32 v142, v56 offset:4352
	ds_write_b32 v142, v57 offset:4624
	ds_write_b32 v142, v58 offset:4896
	ds_write_b32 v142, v59 offset:5168
	ds_write_b32 v142, v60 offset:6528
	ds_write_b32 v142, v61 offset:6800
	ds_write_b32 v142, v62 offset:7072
	ds_write_b32 v142, v63 offset:7344
	ds_write_b32 v142, v32 offset:128
	ds_write_b32 v142, v33 offset:400
	ds_write_b32 v142, v34 offset:672
	ds_write_b32 v142, v35 offset:944
	ds_write_b32 v142, v36 offset:2304
	ds_write_b32 v142, v37 offset:2576
	ds_write_b32 v142, v38 offset:2848
	ds_write_b32 v142, v39 offset:3120
	ds_write_b32 v142, v40 offset:4480
	ds_write_b32 v142, v41 offset:4752
	ds_write_b32 v142, v42 offset:5024
	ds_write_b32 v142, v43 offset:5296
	ds_write_b32 v142, v44 offset:6656
	ds_write_b32 v142, v45 offset:6928
	ds_write_b32 v142, v46 offset:7200
	ds_write_b32 v142, v47 offset:7472
	s_waitcnt lgkmcnt(0)
	ds_read_b32 v32, v148 offset:0
	ds_read_b32 v33, v148 offset:272
	ds_read_b32 v34, v148 offset:544
	ds_read_b32 v35, v148 offset:816
	ds_read_b32 v36, v148 offset:2176
	ds_read_b32 v37, v148 offset:2448
	ds_read_b32 v38, v148 offset:2720
	ds_read_b32 v39, v148 offset:2992
	s_waitcnt lgkmcnt(0)
	v_cvt_pk_bf16_f32 v32, v32, v33
	v_cvt_pk_bf16_f32 v33, v34, v35
	v_cvt_pk_bf16_f32 v34, v36, v37
	v_cvt_pk_bf16_f32 v35, v38, v39
	global_store_dwordx4 v149, v[32:35], s[96:97]
	v_add_u32_e32 v149, s0, v149
	ds_read_b32 v40, v148 offset:64
	ds_read_b32 v41, v148 offset:336
	ds_read_b32 v42, v148 offset:608
	ds_read_b32 v43, v148 offset:880
	ds_read_b32 v44, v148 offset:2240
	ds_read_b32 v45, v148 offset:2512
	ds_read_b32 v46, v148 offset:2784
	ds_read_b32 v47, v148 offset:3056
	s_waitcnt lgkmcnt(0)
	v_cvt_pk_bf16_f32 v40, v40, v41
	v_cvt_pk_bf16_f32 v41, v42, v43
	v_cvt_pk_bf16_f32 v42, v44, v45
	v_cvt_pk_bf16_f32 v43, v46, v47
	global_store_dwordx4 v149, v[40:43], s[96:97]
	v_add_u32_e32 v149, s0, v149
	ds_read_b32 v48, v148 offset:128
	ds_read_b32 v49, v148 offset:400
	ds_read_b32 v50, v148 offset:672
	ds_read_b32 v51, v148 offset:944
	ds_read_b32 v52, v148 offset:2304
	ds_read_b32 v53, v148 offset:2576
	ds_read_b32 v54, v148 offset:2848
	ds_read_b32 v55, v148 offset:3120
	s_waitcnt lgkmcnt(0)
	v_cvt_pk_bf16_f32 v48, v48, v49
	v_cvt_pk_bf16_f32 v49, v50, v51
	v_cvt_pk_bf16_f32 v50, v52, v53
	v_cvt_pk_bf16_f32 v51, v54, v55
	global_store_dwordx4 v149, v[48:51], s[96:97]
	v_add_u32_e32 v149, s0, v149
	ds_read_b32 v56, v148 offset:192
	ds_read_b32 v57, v148 offset:464
	ds_read_b32 v58, v148 offset:736
	ds_read_b32 v59, v148 offset:1008
	ds_read_b32 v60, v148 offset:2368
	ds_read_b32 v61, v148 offset:2640
	ds_read_b32 v62, v148 offset:2912
	ds_read_b32 v63, v148 offset:3184
	s_waitcnt lgkmcnt(0)
	v_cvt_pk_bf16_f32 v56, v56, v57
	v_cvt_pk_bf16_f32 v57, v58, v59
	v_cvt_pk_bf16_f32 v58, v60, v61
	v_cvt_pk_bf16_f32 v59, v62, v63
	global_store_dwordx4 v149, v[56:59], s[96:97]
	v_add_u32_e32 v149, s0, v149
	s_lshl_b32 s1, s0, 2
	s_sub_i32 s1, 64, s1
	v_add_u32_e32 v149, s1, v149
	ds_write_b32 v142, v16 offset:0
	ds_write_b32 v142, v17 offset:272
	ds_write_b32 v142, v18 offset:544
	ds_write_b32 v142, v19 offset:816
	ds_write_b32 v142, v20 offset:2176
	ds_write_b32 v142, v21 offset:2448
	ds_write_b32 v142, v22 offset:2720
	ds_write_b32 v142, v23 offset:2992
	ds_write_b32 v142, v24 offset:4352
	ds_write_b32 v142, v25 offset:4624
	ds_write_b32 v142, v26 offset:4896
	ds_write_b32 v142, v27 offset:5168
	ds_write_b32 v142, v28 offset:6528
	ds_write_b32 v142, v29 offset:6800
	ds_write_b32 v142, v30 offset:7072
	ds_write_b32 v142, v31 offset:7344
	ds_write_b32 v142, v0 offset:128
	ds_write_b32 v142, v1 offset:400
	ds_write_b32 v142, v2 offset:672
	ds_write_b32 v142, v3 offset:944
	ds_write_b32 v142, v4 offset:2304
	ds_write_b32 v142, v5 offset:2576
	ds_write_b32 v142, v6 offset:2848
	ds_write_b32 v142, v7 offset:3120
	ds_write_b32 v142, v8 offset:4480
	ds_write_b32 v142, v9 offset:4752
	ds_write_b32 v142, v10 offset:5024
	ds_write_b32 v142, v11 offset:5296
	ds_write_b32 v142, v12 offset:6656
	ds_write_b32 v142, v13 offset:6928
	ds_write_b32 v142, v14 offset:7200
	ds_write_b32 v142, v15 offset:7472
	s_waitcnt lgkmcnt(0)
	ds_read_b32 v0, v148 offset:0
	ds_read_b32 v1, v148 offset:272
	ds_read_b32 v2, v148 offset:544
	ds_read_b32 v3, v148 offset:816
	ds_read_b32 v4, v148 offset:2176
	ds_read_b32 v5, v148 offset:2448
	ds_read_b32 v6, v148 offset:2720
	ds_read_b32 v7, v148 offset:2992
	s_waitcnt lgkmcnt(0)
	v_cvt_pk_bf16_f32 v0, v0, v1
	v_cvt_pk_bf16_f32 v1, v2, v3
	v_cvt_pk_bf16_f32 v2, v4, v5
	v_cvt_pk_bf16_f32 v3, v6, v7
	global_store_dwordx4 v149, v[0:3], s[96:97]
	v_add_u32_e32 v149, s0, v149
	ds_read_b32 v8, v148 offset:64
	ds_read_b32 v9, v148 offset:336
	ds_read_b32 v10, v148 offset:608
	ds_read_b32 v11, v148 offset:880
	ds_read_b32 v12, v148 offset:2240
	ds_read_b32 v13, v148 offset:2512
	ds_read_b32 v14, v148 offset:2784
	ds_read_b32 v15, v148 offset:3056
	s_waitcnt lgkmcnt(0)
	v_cvt_pk_bf16_f32 v8, v8, v9
	v_cvt_pk_bf16_f32 v9, v10, v11
	v_cvt_pk_bf16_f32 v10, v12, v13
	v_cvt_pk_bf16_f32 v11, v14, v15
	global_store_dwordx4 v149, v[8:11], s[96:97]
	v_add_u32_e32 v149, s0, v149
	ds_read_b32 v16, v148 offset:128
	ds_read_b32 v17, v148 offset:400
	ds_read_b32 v18, v148 offset:672
	ds_read_b32 v19, v148 offset:944
	ds_read_b32 v20, v148 offset:2304
	ds_read_b32 v21, v148 offset:2576
	ds_read_b32 v22, v148 offset:2848
	ds_read_b32 v23, v148 offset:3120
	s_waitcnt lgkmcnt(0)
	v_cvt_pk_bf16_f32 v16, v16, v17
	v_cvt_pk_bf16_f32 v17, v18, v19
	v_cvt_pk_bf16_f32 v18, v20, v21
	v_cvt_pk_bf16_f32 v19, v22, v23
	global_store_dwordx4 v149, v[16:19], s[96:97]
	v_add_u32_e32 v149, s0, v149
	ds_read_b32 v24, v148 offset:192
	ds_read_b32 v25, v148 offset:464
	ds_read_b32 v26, v148 offset:736
	ds_read_b32 v27, v148 offset:1008
	ds_read_b32 v28, v148 offset:2368
	ds_read_b32 v29, v148 offset:2640
	ds_read_b32 v30, v148 offset:2912
	ds_read_b32 v31, v148 offset:3184
	s_waitcnt lgkmcnt(0)
	v_cvt_pk_bf16_f32 v24, v24, v25
	v_cvt_pk_bf16_f32 v25, v26, v27
	v_cvt_pk_bf16_f32 v26, v28, v29
	v_cvt_pk_bf16_f32 v27, v30, v31
	global_store_dwordx4 v149, v[24:27], s[96:97]
	v_add_u32_e32 v149, s0, v149
	s_mov_b64 s[0:1], 0
